# prompt attention loop: back edge rotated (next iteration's counters, ring slots and V fragment base computed in front of the closing wait and barrier; barrier is the loop head)
# baseline (speedup 1.0000x reference)
; template<int THRL,bool PART> __device__ __forceinline__ int attn_unit(const bf16*Qb,const bf16*__restrict__ Kh,const bf16*__restrict__ Vh,bf16*Ob,const int NT,const int vlim_in,char*shm,const int s0,const bool primed,const bf16*nKh,const bf16*nVh,bf16*fuseM,const float lam){
;     ...
;   const bf16*Qw=Qb+(long)(wid*QBLK)*KP;
;   const unsigned lds0=(unsigned)(uintptr_t)shm;
;   float*wsf=(float*)(shm+LDS_WS)+wid*64;
;   const bf16*ksrc=Kh+(long)lane*KP+wid*8;
;   const bf16*vsrc=Vh+(long)(16*(wid&3)+(lane>>2))*KP+(wid>>2)*32+(lane&3)*8;
;   const unsigned kdst=lds0+LDS_K+wid*1024, vdst=lds0+LDS_V+wid*1024;
;     ...
;   const int vb0=(int)(lds0+LDS_V)+((lane>>4)&1)*32+(lane&3)*8+(4*hi+((lane&15)>>2))*64;
;   const int s1=(s0==(NSLOT-1)*SLOTB)?0:s0+SLOTB, s2=(s1==(NSLOT-1)*SLOTB)?0:s1+SLOTB;
;   const char*Kbase=shm+LDS_K+s0; bf16x8 kf[8];
;   const lds_cptr shm3=(lds_cptr)shm; const lds_cptr kp0=shm3+LDS_K+hi*1024+r32*16; const lds_cptr vp0=shm3+LDS_V+((lane>>4)&1)*32+(lane&3)*8+(4*hi+((lane&15)>>2))*64;
;   if(!primed){DMA_K(0,s0);DMA_V(0,s0);DMA_K(1,s1);}
;   bf16x8 qr[4];
;   #pragma unroll
;   for(int d0=0;d0<4;++d0)qr[d0]=*reinterpret_cast<const bf16x8*>(&Qw[(long)r32*KP+d0*16+hi*8]);
;   float zz_=0.f;asm volatile("":"+v"(zz_));
;   float mhat=zz_,l_reg=zz_;f32x16 o[2];
; __global__ void __launch_bounds__(NWAVES * 64, 2) mk_fwd(Args args) {
;     ...
;             for (int i = 0; i < 8; ++i) { const int qb = (i >> 2) ? 15 - s : s, j = (i >> 1) & 1, vh = i & 1;
;                 const bf16* Qp = Qb + (size_t)(b * 4096 + qb * 256) * 512 + (hd * 2 + j) * 64; const bf16* Kp = Kb + (size_t)(b * 4096) * 512 + (hd * 2 + j) * 64; const bf16* Vp = Vb + (size_t)(b * 4096) * 512 + (hd * 2 + vh) * 64;
;                 bf16* Op = ATTO + (size_t)(b * 4096 + qb * 256) * 1024 + ((hd * 2 + j) * 2 + vh) * 64;
;                 bf16* Mp = ((i & 3) == 3) ? H + (size_t)(b * 4096 + qb * 256) * 1024 + 512 + hd * 128 : nullptr;
;                 const bool more = i < 7; const int jn = ((i + 1) >> 1) & 1, vn = (i + 1) & 1;
;                 const bf16* nK = Kb + (size_t)(b * 4096) * 512 + (hd * 2 + jn) * 64; const bf16* nV = Vb + (size_t)(b * 4096) * 512 + (hd * 2 + vn) * 64;
;                 ring0 = attn_body::attn_unit<8, false>((const attn_body::bf16*)Qp, (const attn_body::bf16*)Kp, (const attn_body::bf16*)Vp, (attn_body::bf16*)Op, 4 * (qb + 1), -1, (char*)lds, ring0, primed,
.Lat_j:
	s_lshl_b32 s34, s10, 1
	s_add_i32 s34, s34, s14
	s_add_u32 s18, s66, 0xf300000
	s_addc_u32 s19, s67, 0
	s_lshl_b32 s36, s9, 22
	s_add_u32 s18, s18, s36
	s_addc_u32 s19, s19, 0
	s_lshl_b32 s36, s34, 7
	s_add_u32 s18, s18, s36
	s_addc_u32 s19, s19, 0
	s_add_u32 s20, s66, 0x12200000
	s_addc_u32 s21, s67, 0
	s_lshl_b32 s36, s9, 22
	s_add_u32 s20, s20, s36
	s_addc_u32 s21, s21, 0
	s_lshl_b32 s36, s10, 8
	s_add_u32 s20, s20, s36
	s_addc_u32 s21, s21, 0
	s_add_u32 s22, s66, 0xd100000
	s_addc_u32 s23, s67, 0
	s_lshl_b32 s36, s9, 22
	s_add_u32 s22, s22, s36
	s_addc_u32 s23, s23, 0
	s_lshl_b32 s36, s13, 18
	s_add_u32 s22, s22, s36
	s_addc_u32 s23, s23, 0
	s_lshl_b32 s36, s45, 15
	s_add_u32 s22, s22, s36
	s_addc_u32 s23, s23, 0
	s_lshl_b32 s36, s34, 7
	s_add_u32 s22, s22, s36
	s_addc_u32 s23, s23, 0
	s_mov_b32 s17, 0
	s_mov_b32 s24, 0
	global_load_dwordx4 v[4:7], v234, s[22:23]
	global_load_dwordx4 v[8:11], v234, s[22:23] offset:32
	global_load_dwordx4 v[12:15], v234, s[22:23] offset:64
	global_load_dwordx4 v[16:19], v234, s[22:23] offset:96
	s_mov_b32 s27, 0x0
	s_lshl_b32 s37, s4, 10
	s_add_i32 m0, s37, s27
	s_nop 0
	global_load_lds_dwordx4 v231, s[18:19]
	s_add_u32 s18, s18, 0x10000
	s_addc_u32 s19, s19, 0
	s_mov_b32 s27, 0x2000
	s_lshl_b32 s37, s4, 10
	s_add_i32 m0, s37, s27
	s_nop 0
	global_load_lds_dwordx4 v231, s[18:19]
	s_add_u32 s18, s18, 0x10000
	s_addc_u32 s19, s19, 0
	s_mov_b32 s27, 0x4000
	s_lshl_b32 s37, s4, 10
	s_add_i32 m0, s37, s27
	s_nop 0
	global_load_lds_dwordx4 v231, s[18:19]
	s_add_u32 s18, s18, 0x10000
	s_addc_u32 s19, s19, 0
	s_mov_b32 s27, 0x6000
	s_lshl_b32 s37, s4, 10
	s_add_i32 m0, s37, s27
	s_nop 0
	global_load_lds_dwordx4 v231, s[18:19]
	s_add_u32 s18, s18, 0x10000
	s_addc_u32 s19, s19, 0
	s_mov_b32 s29, 0x8000
	s_lshl_b32 s37, s4, 10
	s_add_i32 m0, s37, s29
	s_nop 0
	global_load_lds_dwordx4 v232, s[20:21]
	s_add_i32 m0, m0, 0x2000
	s_nop 0
	global_load_lds_dwordx4 v233, s[20:21]
	s_add_u32 s20, s20, 0x10000
	s_addc_u32 s21, s21, 0
	s_mov_b32 s29, 0xc000
	s_lshl_b32 s37, s4, 10
	s_add_i32 m0, s37, s29
	s_nop 0
	global_load_lds_dwordx4 v232, s[20:21]
	s_add_i32 m0, m0, 0x2000
	s_nop 0
	global_load_lds_dwordx4 v233, s[20:21]
	s_add_u32 s20, s20, 0x10000
	s_addc_u32 s21, s21, 0
	v_mov_b32_e32 v148, 0
	v_mov_b32_e32 v149, 0
	v_mov_b32_e32 v150, 0
	v_mov_b32_e32 v151, 0
	v_mov_b32_e32 v152, 0
	v_mov_b32_e32 v153, 0
	v_mov_b32_e32 v154, 0
	v_mov_b32_e32 v155, 0
	v_mov_b32_e32 v156, 0
	v_mov_b32_e32 v157, 0
	v_mov_b32_e32 v158, 0
	v_mov_b32_e32 v159, 0
	v_mov_b32_e32 v160, 0
	v_mov_b32_e32 v161, 0
	v_mov_b32_e32 v162, 0
	v_mov_b32_e32 v163, 0
	v_mov_b32_e32 v164, 0
	v_mov_b32_e32 v165, 0
	v_mov_b32_e32 v166, 0
	v_mov_b32_e32 v167, 0
	v_mov_b32_e32 v168, 0
	v_mov_b32_e32 v169, 0
	v_mov_b32_e32 v170, 0
	v_mov_b32_e32 v171, 0
	v_mov_b32_e32 v172, 0
	v_mov_b32_e32 v173, 0
	v_mov_b32_e32 v174, 0
	v_mov_b32_e32 v175, 0
	v_mov_b32_e32 v176, 0
	v_mov_b32_e32 v177, 0
	v_mov_b32_e32 v178, 0
	v_mov_b32_e32 v179, 0
	v_mov_b32_e32 v180, 0
	v_mov_b32_e32 v181, 0
	v_mov_b32_e32 v182, 0
	v_mov_b32_e32 v183, 0
	v_mov_b32_e32 v184, 0
	v_mov_b32_e32 v185, 0
	v_mov_b32_e32 v186, 0
	v_mov_b32_e32 v187, 0
	v_mov_b32_e32 v188, 0
	v_mov_b32_e32 v189, 0
	v_mov_b32_e32 v190, 0
	v_mov_b32_e32 v191, 0
	v_mov_b32_e32 v192, 0
	v_mov_b32_e32 v193, 0
	v_mov_b32_e32 v194, 0
	v_mov_b32_e32 v195, 0
	v_mov_b32_e32 v196, 0
	v_mov_b32_e32 v197, 0
	v_mov_b32_e32 v198, 0
	v_mov_b32_e32 v199, 0
	v_mov_b32_e32 v200, 0
	v_mov_b32_e32 v201, 0
	v_mov_b32_e32 v202, 0
	v_mov_b32_e32 v203, 0
	v_mov_b32_e32 v204, 0
	v_mov_b32_e32 v205, 0
	v_mov_b32_e32 v206, 0
	v_mov_b32_e32 v207, 0
	v_mov_b32_e32 v208, 0
	v_mov_b32_e32 v209, 0
	v_mov_b32_e32 v210, 0
	v_mov_b32_e32 v211, 0
	v_mov_b32_e32 v84, 0
	v_mov_b32_e32 v85, 0
	v_mov_b32_e32 v86, 0
	v_mov_b32_e32 v87, 0
	v_mov_b32_e32 v88, 0
	v_mov_b32_e32 v89, 0
	v_mov_b32_e32 v90, 0
	v_mov_b32_e32 v91, 0
	v_mov_b32_e32 v92, 0
	v_mov_b32_e32 v93, 0
	v_mov_b32_e32 v94, 0
	v_mov_b32_e32 v95, 0
	v_mov_b32_e32 v96, 0
	v_mov_b32_e32 v97, 0
	v_mov_b32_e32 v98, 0
	v_mov_b32_e32 v99, 0
	v_mov_b32_e32 v212, 0
	v_mov_b32_e32 v213, 0
	s_waitcnt vmcnt(0)
	s_barrier
	ds_read_b128 v[20:23], v235
	ds_read_b128 v[24:27], v236
	ds_read_b128 v[28:31], v237
	ds_read_b128 v[32:35], v238
	ds_read_b128 v[36:39], v235 offset:4096
	ds_read_b128 v[40:43], v236 offset:4096
	ds_read_b128 v[44:47], v237 offset:4096
	ds_read_b128 v[48:51], v238 offset:4096
	s_add_i32 s26, s24, 1
	s_and_b32 s26, s26, 3
	s_lshl_b32 s26, s26, 13
	s_lshl_b32 s27, s24, 13
	s_add_i32 s28, s24, 3
	s_and_b32 s28, s28, 3
	s_lshl_b32 s28, s28, 14
	s_add_i32 s28, s28, 0x8000
	s_add_i32 s29, s24, 2
	s_and_b32 s29, s29, 3
	s_lshl_b32 s29, s29, 14
	s_add_i32 s29, s29, 0x8000
.Lat_t1:
	s_cmp_lt_u32 s17, s16
	s_cbranch_scc0 .Lat_last4
	s_cmp_eq_u32 s17, 0
	s_cbranch_scc1 .Lat_first3
	ds_read_b64_tr_b16 v[116:117], v218 offset:0
	ds_read_b64_tr_b16 v[118:119], v218 offset:512
	v_mfma_f32_32x32x16_bf16 v[52:67], v[20:23], v[4:7], v[84:99]
	ds_read_b64_tr_b16 v[120:121], v218 offset:4096
	ds_read_b64_tr_b16 v[122:123], v218 offset:4608
	v_mfma_f32_32x32x16_bf16 v[52:67], v[24:27], v[8:11], v[52:67]
	ds_read_b64_tr_b16 v[124:125], v218 offset:8192
	ds_read_b64_tr_b16 v[126:127], v218 offset:8704
	v_mfma_f32_32x32x16_bf16 v[52:67], v[28:31], v[12:15], v[52:67]
	ds_read_b64_tr_b16 v[128:129], v218 offset:12288
	ds_read_b64_tr_b16 v[130:131], v218 offset:12800
	v_mfma_f32_32x32x16_bf16 v[52:67], v[32:35], v[16:19], v[52:67]
	ds_read_b64_tr_b16 v[132:133], v218 offset:1024
	ds_read_b64_tr_b16 v[134:135], v218 offset:1536
	v_mfma_f32_32x32x16_bf16 v[68:83], v[36:39], v[4:7], v[84:99]
	ds_read_b64_tr_b16 v[136:137], v218 offset:5120
	ds_read_b64_tr_b16 v[138:139], v218 offset:5632
	v_mfma_f32_32x32x16_bf16 v[68:83], v[40:43], v[8:11], v[68:83]
	ds_read_b64_tr_b16 v[140:141], v218 offset:9216
	ds_read_b64_tr_b16 v[142:143], v218 offset:9728
	v_mfma_f32_32x32x16_bf16 v[68:83], v[44:47], v[12:15], v[68:83]
	ds_read_b64_tr_b16 v[144:145], v218 offset:13312
	ds_read_b64_tr_b16 v[146:147], v218 offset:13824
	v_mfma_f32_32x32x16_bf16 v[68:83], v[48:51], v[16:19], v[68:83]
	s_nop 7
	s_nop 7
	v_max3_f32 v219, v52, v53, v54
	v_max3_f32 v220, v55, v56, v57
	v_max3_f32 v219, v219, v58, v59
	v_max3_f32 v220, v220, v60, v61
	v_max3_f32 v219, v219, v62, v63
	v_max3_f32 v220, v220, v64, v65
	v_max3_f32 v219, v219, v66, v67
	v_max3_f32 v220, v220, v68, v69
	v_max3_f32 v219, v219, v70, v71
	v_max3_f32 v220, v220, v72, v73
	v_max3_f32 v219, v219, v74, v75
	v_max3_f32 v220, v220, v76, v77
	v_max3_f32 v219, v219, v78, v79
	v_max3_f32 v220, v220, v80, v81
	v_max3_f32 v219, v219, v82, v83
	v_max_f32_e32 v214, v219, v220
	v_mov_b32_e32 v219, v214
	s_nop 1
	v_permlane32_swap_b32_e32 v214, v219
	v_max_f32_e32 v214, v214, v219
	s_mov_b32 s54, 0
	v_cmp_lt_f32_e32 vcc, s48, v214
	s_nop 0
	s_cmp_lg_u64 vcc, 0
	s_cbranch_scc0 .Lat_nores6
	v_max_f32_e32 v214, 0, v214
	v_add_f32_e32 v212, v212, v214
	v_sub_f32_e32 v52, v52, v214
	v_sub_f32_e32 v53, v53, v214
	v_sub_f32_e32 v54, v54, v214
	v_sub_f32_e32 v55, v55, v214
	v_sub_f32_e32 v56, v56, v214
	v_sub_f32_e32 v57, v57, v214
	v_sub_f32_e32 v58, v58, v214
	v_sub_f32_e32 v59, v59, v214
	v_sub_f32_e32 v60, v60, v214
	v_sub_f32_e32 v61, v61, v214
	v_sub_f32_e32 v62, v62, v214
	v_sub_f32_e32 v63, v63, v214
	v_sub_f32_e32 v64, v64, v214
	v_sub_f32_e32 v65, v65, v214
	v_sub_f32_e32 v66, v66, v214
	v_sub_f32_e32 v67, v67, v214
	v_sub_f32_e32 v68, v68, v214
	v_sub_f32_e32 v69, v69, v214
	v_sub_f32_e32 v70, v70, v214
	v_sub_f32_e32 v71, v71, v214
	v_sub_f32_e32 v72, v72, v214
	v_sub_f32_e32 v73, v73, v214
	v_sub_f32_e32 v74, v74, v214
	v_sub_f32_e32 v75, v75, v214
	v_sub_f32_e32 v76, v76, v214
	v_sub_f32_e32 v77, v77, v214
	v_sub_f32_e32 v78, v78, v214
	v_sub_f32_e32 v79, v79, v214
	v_sub_f32_e32 v80, v80, v214
	v_sub_f32_e32 v81, v81, v214
	v_sub_f32_e32 v82, v82, v214
	v_sub_f32_e32 v83, v83, v214
	v_xor_b32_e32 v84, 0x80000000, v212
	v_xor_b32_e32 v85, 0x80000000, v212
	v_xor_b32_e32 v86, 0x80000000, v212
	v_xor_b32_e32 v87, 0x80000000, v212
	v_xor_b32_e32 v88, 0x80000000, v212
	v_xor_b32_e32 v89, 0x80000000, v212
	v_xor_b32_e32 v90, 0x80000000, v212
	v_xor_b32_e32 v91, 0x80000000, v212
	v_xor_b32_e32 v92, 0x80000000, v212
	v_xor_b32_e32 v93, 0x80000000, v212
	v_xor_b32_e32 v94, 0x80000000, v212
	v_xor_b32_e32 v95, 0x80000000, v212
	v_xor_b32_e32 v96, 0x80000000, v212
	v_xor_b32_e32 v97, 0x80000000, v212
	v_xor_b32_e32 v98, 0x80000000, v212
	v_xor_b32_e32 v99, 0x80000000, v212
	v_exp_f32_e64 v215, -v214
	s_mov_b32 s54, 1
	v_add_u32_e32 v222, v230, v240
	v_mul_f32_e32 v213, v213, v215
	ds_write_b32 v222, v215 offset:0

; #define SBAR() __builtin_amdgcn_sched_barrier(0)
; __device__ __forceinline__ void pv(f32x16*o,int vb,bf16x8 pa0,bf16x8 pa1,bf16x8 pa2,bf16x8 pa3){
;   #pragma unroll
;   for(int d0=0;d0<2;++d0){s16x4 lo[4],hi[4];
;     #pragma unroll
;     for(int ks=0;ks<4;++ks){
;       asm volatile("ds_read_b64_tr_b16 %0,%1 offset:%c2":"=&v"(lo[ks]):"v"(vb),"i"(d0*4096+ks*1024):"memory");
;       asm volatile("ds_read_b64_tr_b16 %0,%1 offset:%c2":"=&v"(hi[ks]):"v"(vb),"i"(d0*4096+ks*1024+512):"memory");}
;     asm volatile("s_waitcnt lgkmcnt(0)":::"memory");SBAR();
;     ...
;     o[d0]=__builtin_amdgcn_mfma_f32_32x32x16_bf16(pa0,PK(0),o[d0],0,0,0);
;     o[d0]=__builtin_amdgcn_mfma_f32_32x32x16_bf16(pa1,PK(1),o[d0],0,0,0);
;     o[d0]=__builtin_amdgcn_mfma_f32_32x32x16_bf16(pa2,PK(2),o[d0],0,0,0);
;     o[d0]=__builtin_amdgcn_mfma_f32_32x32x16_bf16(pa3,PK(3),o[d0],0,0,0);
;     ...
;   }
.Lat_last4:
	s_mov_b32 s54, 0
	s_cmp_eq_u32 s17, s16
	s_cbranch_scc0 .Lat_end5
	ds_read_b64_tr_b16 v[116:117], v218 offset:0
	ds_read_b64_tr_b16 v[118:119], v218 offset:512
	ds_read_b64_tr_b16 v[120:121], v218 offset:4096
	ds_read_b64_tr_b16 v[122:123], v218 offset:4608
	ds_read_b64_tr_b16 v[124:125], v218 offset:8192
	ds_read_b64_tr_b16 v[126:127], v218 offset:8704
	ds_read_b64_tr_b16 v[128:129], v218 offset:12288
	ds_read_b64_tr_b16 v[130:131], v218 offset:12800
	ds_read_b64_tr_b16 v[132:133], v218 offset:1024
	ds_read_b64_tr_b16 v[134:135], v218 offset:1536
	ds_read_b64_tr_b16 v[136:137], v218 offset:5120
	ds_read_b64_tr_b16 v[138:139], v218 offset:5632
	ds_read_b64_tr_b16 v[140:141], v218 offset:9216
	ds_read_b64_tr_b16 v[142:143], v218 offset:9728
	ds_read_b64_tr_b16 v[144:145], v218 offset:13312
	ds_read_b64_tr_b16 v[146:147], v218 offset:13824
	s_waitcnt lgkmcnt(0)
	v_mfma_f32_32x32x16_bf16 v[148:163], v[100:103], v[116:119], v[148:163]
	ds_read_b64_tr_b16 v[116:117], v218 offset:2048
	ds_read_b64_tr_b16 v[118:119], v218 offset:2560
	v_mfma_f32_32x32x16_bf16 v[164:179], v[100:103], v[120:123], v[164:179]
	ds_read_b64_tr_b16 v[120:121], v218 offset:6144
	ds_read_b64_tr_b16 v[122:123], v218 offset:6656
	v_mfma_f32_32x32x16_bf16 v[180:195], v[100:103], v[124:127], v[180:195]
	ds_read_b64_tr_b16 v[124:125], v218 offset:10240
	ds_read_b64_tr_b16 v[126:127], v218 offset:10752
	v_mfma_f32_32x32x16_bf16 v[196:211], v[100:103], v[128:131], v[196:211]
	ds_read_b64_tr_b16 v[128:129], v218 offset:14336
	ds_read_b64_tr_b16 v[130:131], v218 offset:14848
	v_mfma_f32_32x32x16_bf16 v[148:163], v[104:107], v[132:135], v[148:163]
	ds_read_b64_tr_b16 v[132:133], v218 offset:3072
	ds_read_b64_tr_b16 v[134:135], v218 offset:3584
	v_mfma_f32_32x32x16_bf16 v[164:179], v[104:107], v[136:139], v[164:179]
	ds_read_b64_tr_b16 v[136:137], v218 offset:7168
	ds_read_b64_tr_b16 v[138:139], v218 offset:7680
	v_mfma_f32_32x32x16_bf16 v[180:195], v[104:107], v[140:143], v[180:195]
	ds_read_b64_tr_b16 v[140:141], v218 offset:11264
	ds_read_b64_tr_b16 v[142:143], v218 offset:11776
	v_mfma_f32_32x32x16_bf16 v[196:211], v[104:107], v[144:147], v[196:211]
	ds_read_b64_tr_b16 v[144:145], v218 offset:15360
	ds_read_b64_tr_b16 v[146:147], v218 offset:15872
	s_waitcnt lgkmcnt(14)
	v_mfma_f32_32x32x16_bf16 v[148:163], v[108:111], v[116:119], v[148:163]
	s_waitcnt lgkmcnt(12)
	v_mfma_f32_32x32x16_bf16 v[164:179], v[108:111], v[120:123], v[164:179]
	s_waitcnt lgkmcnt(10)
	v_mfma_f32_32x32x16_bf16 v[180:195], v[108:111], v[124:127], v[180:195]
	s_waitcnt lgkmcnt(8)
	v_mfma_f32_32x32x16_bf16 v[196:211], v[108:111], v[128:131], v[196:211]
	s_waitcnt lgkmcnt(6)
	v_mfma_f32_32x32x16_bf16 v[148:163], v[112:115], v[132:135], v[148:163]
	s_waitcnt lgkmcnt(4)
	v_mfma_f32_32x32x16_bf16 v[164:179], v[112:115], v[136:139], v[164:179]
	s_waitcnt lgkmcnt(2)
	v_mfma_f32_32x32x16_bf16 v[180:195], v[112:115], v[140:143], v[180:195]
	s_waitcnt lgkmcnt(0)
	v_mfma_f32_32x32x16_bf16 v[196:211], v[112:115], v[144:147], v[196:211]

; #define WAIT_BAR(N) asm volatile("s_waitcnt vmcnt(" #N ") lgkmcnt(0)\n\ts_barrier":::"memory")
;   #define RESC() do{ if(resc){ asm volatile("s_waitcnt lgkmcnt(0)":::"memory"); \
;       _Pragma("unroll") for(int d_=0;d_<2;++d_) _Pragma("unroll") for(int r=0;r<16;++r)o[d_][r]*=wsf[crow(r,hi)]; } }while(0)
;   #define ROT() do{sl_prev=sl_cur;sl_cur=sl_next;sl_next=(sl_next==(NSLOT-1)*SLOTB)?0:sl_next+SLOTB;}while(0)
; template<int THRL,bool PART> __device__ __forceinline__ int attn_unit(const bf16*Qb,const bf16*__restrict__ Kh,const bf16*__restrict__ Vh,bf16*Ob,const int NT,const int vlim_in,char*shm,const int s0,const bool primed,const bf16*nKh,const bf16*nVh,bf16*fuseM,const float lam){
;     ...
;     STEP(pB0,pB1,pA0,pA1,t,true,true,true);     WAIT_BAR(2); RESC(); ROT();
.Lat_nor7:
	s_add_i32 s34, s17, 4
	s_cmp_lt_u32 s34, s15
	s_cbranch_scc0 .Lat_dn8
	s_lshl_b32 s37, s4, 10
	s_add_i32 m0, s37, s27
	s_nop 0
	global_load_lds_dwordx4 v231, s[18:19]
	s_add_u32 s18, s18, 0x10000
	s_addc_u32 s19, s19, 0
	s_lshl_b32 s37, s4, 10
	s_add_i32 m0, s37, s29
	s_nop 0
	global_load_lds_dwordx4 v232, s[20:21]
	s_add_i32 m0, m0, 0x2000
	s_nop 0
	global_load_lds_dwordx4 v233, s[20:21]
	s_add_u32 s20, s20, 0x10000
	s_addc_u32 s21, s21, 0
	s_add_i32 s24, s24, 1
	s_and_b32 s24, s24, 3
	s_add_i32 s26, s24, 1
	s_and_b32 s26, s26, 3
	s_lshl_b32 s26, s26, 13
	s_lshl_b32 s27, s24, 13
	s_add_i32 s28, s24, 3
	s_and_b32 s28, s28, 3
	s_lshl_b32 s28, s28, 14
	s_add_i32 s28, s28, 0x8000
	s_add_i32 s29, s24, 2
	s_and_b32 s29, s29, 3
	s_lshl_b32 s29, s29, 14
	s_add_i32 s29, s29, 0x8000
	v_add_u32_e32 v218, s28, v229
	s_add_i32 s17, s17, 1
	s_cmp_le_u32 s17, s15
	s_waitcnt vmcnt(6) lgkmcnt(0)
	s_branch .Lat_bar9

; #define WAIT_BAR(N) asm volatile("s_waitcnt vmcnt(" #N ") lgkmcnt(0)\n\ts_barrier":::"memory")
;   #define RESC() do{ if(resc){ asm volatile("s_waitcnt lgkmcnt(0)":::"memory"); \
;       _Pragma("unroll") for(int d_=0;d_<2;++d_) _Pragma("unroll") for(int r=0;r<16;++r)o[d_][r]*=wsf[crow(r,hi)]; } }while(0)
;   #define ROT() do{sl_prev=sl_cur;sl_cur=sl_next;sl_next=(sl_next==(NSLOT-1)*SLOTB)?0:sl_next+SLOTB;}while(0)
;   #define ENDW(tt) do{ if((tt)+3<NT){WAIT_BAR(2);} else if((tt)+2<NT){WAIT_BAR(1);} else {WAIT_BAR(0);} }while(0)
; template<int THRL,bool PART> __device__ __forceinline__ int attn_unit(const bf16*Qb,const bf16*__restrict__ Kh,const bf16*__restrict__ Vh,bf16*Ob,const int NT,const int vlim_in,char*shm,const int s0,const bool primed,const bf16*nKh,const bf16*nVh,bf16*fuseM,const float lam){
;     ...
;     STEP(pB0,pB1,pA0,pA1,t,true,true,true);     WAIT_BAR(2); RESC(); ROT();
;     STEP(pA0,pA1,pB0,pB1,t+1,true,true,true);   WAIT_BAR(2); RESC(); ROT();
;   }
;     ...
;   for(;t+1<NT;t+=2){
;     STEP(pB0,pB1,pA0,pA1,t,(t+3<NT),(t+1<NT),(t+1<NT));       ENDW(t);   RESC(); ROT();
;     STEP(pA0,pA1,pB0,pB1,t+1,(t+4<NT),(t+2<NT),(t+2<NT));     ENDW(t+1); RESC(); ROT();
;   }
;   if(nKh){ const bf16*nks=nKh+(long)lane*KP+wid*8; const bf16*nvs=nVh+(long)(16*(wid&3)+(lane>>2))*KP+(wid>>2)*32+(lane&3)*8;
;     const int a0=sl_next, a1=(a0==(NSLOT-1)*SLOTB)?0:a0+SLOTB, a2=(a1==(NSLOT-1)*SLOTB)?0:a1+SLOTB;
;     glds16(nks,(unsigned)__builtin_amdgcn_readfirstlane(kdst+a0)); glds16(nvs,(unsigned)__builtin_amdgcn_readfirstlane(vdst+a0));
;     glds16(nks+(long)KVBLK*KP,(unsigned)__builtin_amdgcn_readfirstlane(kdst+a1)); glds16(nks+2L*KVBLK*KP,(unsigned)__builtin_amdgcn_readfirstlane(kdst+a2)); }
;   STEP(pB0,pB1,pA0,pA1,NT-1,false,false,false); RESC();
.Lat_dv10:
	s_add_i32 s24, s24, 1
	s_and_b32 s24, s24, 3
	s_add_i32 s26, s24, 1
	s_and_b32 s26, s26, 3
	s_lshl_b32 s26, s26, 13
	s_lshl_b32 s27, s24, 13
	s_add_i32 s28, s24, 3
	s_and_b32 s28, s28, 3
	s_lshl_b32 s28, s28, 14
	s_add_i32 s28, s28, 0x8000
	s_add_i32 s29, s24, 2
	s_and_b32 s29, s29, 3
	s_lshl_b32 s29, s29, 14
	s_add_i32 s29, s29, 0x8000
	v_add_u32_e32 v218, s28, v229
	s_add_i32 s17, s17, 1
	s_cmp_le_u32 s17, s15
	s_waitcnt vmcnt(0) lgkmcnt(0)
.Lat_bar9:
	s_barrier
	s_cbranch_scc1 .Lat_t1
	v_add_u32_e32 v224, 0x1000, v239
	v_add_u32_e32 v225, 0x2000, v239
	v_add_u32_e32 v226, 0x3000, v239
	s_cmp_eq_u32 s14, 0
	s_cbranch_scc1 .Lat_nopre13
	global_load_dwordx4 v[20:23], v239, s[52:53] sc1
	global_load_dwordx4 v[24:27], v239, s[52:53] offset:1024 sc1
	global_load_dwordx4 v[28:31], v239, s[52:53] offset:2048 sc1
	global_load_dwordx4 v[32:35], v239, s[52:53] offset:3072 sc1
	global_load_dwordx4 v[36:39], v224, s[52:53] sc1
	global_load_dwordx4 v[40:43], v224, s[52:53] offset:1024 sc1
	global_load_dwordx4 v[44:47], v224, s[52:53] offset:2048 sc1
	global_load_dwordx4 v[48:51], v224, s[52:53] offset:3072 sc1
	global_load_dwordx4 v[52:55], v225, s[52:53] sc1
	global_load_dwordx4 v[56:59], v225, s[52:53] offset:1024 sc1
	global_load_dwordx4 v[60:63], v225, s[52:53] offset:2048 sc1
	global_load_dwordx4 v[64:67], v225, s[52:53] offset:3072 sc1
	global_load_dwordx4 v[68:71], v226, s[52:53] sc1
	global_load_dwordx4 v[72:75], v226, s[52:53] offset:1024 sc1
	global_load_dwordx4 v[76:79], v226, s[52:53] offset:2048 sc1
	global_load_dwordx4 v[80:83], v226, s[52:53] offset:3072 sc1
